# gate/up K-loop: on the tile's last K iteration also touch the two sh (per-column shift) lines the epilogue reads first (L2-cold every tile); amplified probe -5 us per gate/up phase
# speedup vs baseline: 1.0057x; 1.0013x over previous
; #define PG8_STAGE(bufoff, gbase, voff) do { _Pragma("unroll") for (int _i = 0; _i < 2; ++_i) \
;         __builtin_amdgcn_global_load_lds((const unsigned*)((const char*)(gbase) + (voff)[_i]), (PG8_LAS unsigned*)(lds + (bufoff) + ldsw + _i * 8192), 16, 0, 0); } while (0)
; #define PG8_LDA(dst, b, h) do { _Pragma("unroll") for (int m = 0; m < 4; ++m) _Pragma("unroll") for (int k = 0; k < 2; ++k) dst[m][k] = *(const PG8_LAS bf16x8*)(lds + PG8_SA(b, h) + aoff + m * 2048 + k * 1024); } while (0)
; #define PG8_LDB(dst, b, h) do { _Pragma("unroll") for (int n = 0; n < 2; ++n) _Pragma("unroll") for (int k = 0; k < 2; ++k) dst[n][k] = *(const PG8_LAS bf16x8*)(lds + PG8_SB(b, h) + boff + n * 2048 + k * 1024); } while (0)
; #define PG8_MMA(ai, bj, At, Bt) do { __builtin_amdgcn_s_setprio(1); _Pragma("unroll") for (int m = 0; m < 4; ++m) _Pragma("unroll") for (int n = 0; n < 2; ++n) _Pragma("unroll") for (int k = 0; k < 2; ++k) \
;         acc[ai][bj][m][n] = __builtin_amdgcn_mfma_f32_16x16x32_bf16(Bt[n][k], At[m][k], acc[ai][bj][m][n], 0, 0, 0); __builtin_amdgcn_s_setprio(0); } while (0)
; #define PG8_WAIT_V(n) asm volatile("s_waitcnt vmcnt(" #n ")" ::: "memory")
; #define PG8_WAIT_L(n) asm volatile("s_waitcnt lgkmcnt(" #n ")" ::: "memory")
; #define PG8_BAR __builtin_amdgcn_s_barrier()
; template <class Epi, class Sched, bool ALIGN_EPI = false, bool SP2 = false, bool ATILED = false, bool BTILED = false>
; __device__ __forceinline__ void gemm_phase(PG8_LAS unsigned char* lds, const Gemm g, const Sched& S, const Epi& E, const int tid) {
;     ...
;             const bool last = (t == nt - 2);
;             const char* a1 = cA + (size_t)(t + 1) * kstepA;
;             const char* a2 = last ? nA : cA + (size_t)(t + 2) * kstepA; const char* b2 = last ? nB : cB + (size_t)(t + 2) * kstepB;
;             const char* a3 = a2 + kstepA; const char* b3 = b2 + kstepB;
;             if (last && has_next) S.a_ready(nxt);
;             if constexpr (SP2) {
;             PG8_LDB(B0, 0, 0); PG8_LDB(B1, 0, 1); PG8_SCHED; PG8_LDA(At, 0, 0); PG8_STAGE(PG8_SA(1, 1), a1 + hstepA, voffA);
;             PG8_WAIT_V(8); PG8_WAIT_L(0); PG8_BAR; PG8_MMA(0, 0, At, B0); PG8_MMA(0, 1, At, B1); PG8_BAR; PG8_SCHED;
;             PG8_LDA(At, 0, 1); PG8_STAGE(PG8_SB(0, 0), b2, voffB); PG8_STAGE(PG8_SB(0, 1), b2 + hstepB, voffB); PG8_STAGE(PG8_SA(0, 0), a2, voffA);
.LBB0_166:
	s_add_u32 s54, s52, 0x4000
	s_addc_u32 s55, s53, 0
	s_cmp_eq_u32 s76, 12
	s_cselect_b32 s58, s19, s54
	s_cselect_b32 s59, s15, s55
	s_cselect_b32 s56, s29, s74
	s_cselect_b32 s57, s13, s75
	s_add_u32 s54, s58, 0x8000
	s_addc_u32 s55, s59, 0
	s_add_i32 s77, 0, 0x10000
	s_add_i32 s80, 0, 0x14000
	v_add_u32_e32 v82, s77, v1
	v_add_u32_e32 v195, s80, v1
	ds_read_b128 v[66:69], v82
	ds_read_b128 v[70:73], v82 offset:1024
	ds_read_b128 v[78:81], v82 offset:2048
	ds_read_b128 v[82:85], v82 offset:3072
	ds_read_b128 v[180:183], v195
	ds_read_b128 v[186:189], v195 offset:1024
	ds_read_b128 v[190:193], v195 offset:2048
	ds_read_b128 v[196:199], v195 offset:3072
	v_lshl_add_u64 v[228:229], s[52:53], 0, v[174:175]
	s_add_i32 m0, s66, 0xc000
	ds_read_b128 v[200:203], v155
	ds_read_b128 v[204:207], v155 offset:1024
	ds_read_b128 v[208:211], v155 offset:2048
	ds_read_b128 v[212:215], v155 offset:3072
	ds_read_b128 v[216:219], v155 offset:4096
	ds_read_b128 v[220:223], v155 offset:5120
	ds_read_b128 v[224:227], v155 offset:6144
	ds_read_b128 v[242:245], v155 offset:7168
	global_load_lds_dwordx4 v[228:229], off
	v_lshl_add_u64 v[228:229], s[52:53], 0, v[176:177]
	s_add_i32 m0, s66, 0xe000
	s_nop 0
	global_load_lds_dwordx4 v[228:229], off
	s_waitcnt vmcnt(8)
	s_waitcnt lgkmcnt(0)
	s_barrier
	s_setprio 1
	s_waitcnt lgkmcnt(0)
	v_mfma_f32_16x16x32_bf16 v[142:145], v[66:69], v[200:203], v[142:145]
	v_mfma_f32_16x16x32_bf16 v[138:141], v[78:81], v[200:203], v[138:141]
	v_mfma_f32_16x16x32_bf16 v[126:129], v[66:69], v[208:211], v[126:129]
	v_mfma_f32_16x16x32_bf16 v[118:121], v[78:81], v[208:211], v[118:121]
	v_mfma_f32_16x16x32_bf16 v[110:113], v[66:69], v[216:219], v[110:113]
	v_mfma_f32_16x16x32_bf16 v[102:105], v[78:81], v[216:219], v[102:105]
	v_mfma_f32_16x16x32_bf16 v[94:97], v[66:69], v[224:227], v[94:97]
	v_mfma_f32_16x16x32_bf16 v[86:89], v[78:81], v[224:227], v[86:89]
	v_mfma_f32_16x16x32_bf16 v[142:145], v[70:73], v[204:207], v[142:145]
	v_mfma_f32_16x16x32_bf16 v[138:141], v[82:85], v[204:207], v[138:141]
	v_mfma_f32_16x16x32_bf16 v[126:129], v[70:73], v[212:215], v[126:129]
	v_mfma_f32_16x16x32_bf16 v[118:121], v[82:85], v[212:215], v[118:121]
	v_mfma_f32_16x16x32_bf16 v[110:113], v[70:73], v[220:223], v[110:113]
	v_mfma_f32_16x16x32_bf16 v[102:105], v[82:85], v[220:223], v[102:105]
	v_mfma_f32_16x16x32_bf16 v[94:97], v[70:73], v[242:245], v[94:97]
	v_mfma_f32_16x16x32_bf16 v[86:89], v[82:85], v[242:245], v[86:89]
	s_setprio 0
	s_setprio 1
	v_mfma_f32_16x16x32_bf16 v[134:137], v[180:183], v[200:203], v[134:137]
	v_mfma_f32_16x16x32_bf16 v[130:133], v[190:193], v[200:203], v[130:133]
	v_mfma_f32_16x16x32_bf16 v[122:125], v[180:183], v[208:211], v[122:125]
	v_mfma_f32_16x16x32_bf16 v[114:117], v[190:193], v[208:211], v[114:117]
	v_mfma_f32_16x16x32_bf16 v[106:109], v[180:183], v[216:219], v[106:109]
	v_mfma_f32_16x16x32_bf16 v[98:101], v[190:193], v[216:219], v[98:101]
	v_mfma_f32_16x16x32_bf16 v[90:93], v[180:183], v[224:227], v[90:93]
	v_mfma_f32_16x16x32_bf16 v[74:77], v[190:193], v[224:227], v[74:77]
	v_mfma_f32_16x16x32_bf16 v[134:137], v[186:189], v[204:207], v[134:137]
	v_mfma_f32_16x16x32_bf16 v[130:133], v[196:199], v[204:207], v[130:133]
	v_mfma_f32_16x16x32_bf16 v[122:125], v[186:189], v[212:215], v[122:125]
	v_mfma_f32_16x16x32_bf16 v[114:117], v[196:199], v[212:215], v[114:117]
	v_mfma_f32_16x16x32_bf16 v[106:109], v[186:189], v[220:223], v[106:109]
	v_mfma_f32_16x16x32_bf16 v[98:101], v[196:199], v[220:223], v[98:101]
	v_mfma_f32_16x16x32_bf16 v[90:93], v[186:189], v[242:245], v[90:93]
	v_mfma_f32_16x16x32_bf16 v[74:77], v[196:199], v[242:245], v[74:77]
	s_setprio 0
	s_barrier
	s_add_i32 s77, s77, s64
	v_lshl_add_u64 v[228:229], s[56:57], 0, v[150:151]
	s_mov_b32 m0, s77
	ds_read_b128 v[200:203], v155 offset:16384
	ds_read_b128 v[204:207], v155 offset:17408
	ds_read_b128 v[208:211], v155 offset:18432
	ds_read_b128 v[212:215], v155 offset:19456
	ds_read_b128 v[216:219], v155 offset:20480
	ds_read_b128 v[220:223], v155 offset:21504
	ds_read_b128 v[224:227], v155 offset:22528
	ds_read_b128 v[242:245], v155 offset:23552
	global_load_lds_dwordx4 v[228:229], off
	s_add_i32 m0, s77, 0x2000
	s_add_u32 s78, s56, 0x4000
	v_lshl_add_u64 v[228:229], s[56:57], 0, v[146:147]
	s_addc_u32 s79, s57, 0
	s_add_i32 s77, s80, s64
	global_load_lds_dwordx4 v[228:229], off
	v_lshl_add_u64 v[228:229], s[78:79], 0, v[150:151]
	s_mov_b32 m0, s77
	s_nop 0
	global_load_lds_dwordx4 v[228:229], off
	v_lshl_add_u64 v[228:229], s[78:79], 0, v[146:147]
	s_add_i32 m0, s77, 0x2000
	s_nop 0
	global_load_lds_dwordx4 v[228:229], off
	v_lshl_add_u64 v[228:229], s[58:59], 0, v[152:153]
	s_mov_b32 m0, s66
	s_nop 0
	global_load_lds_dwordx4 v[228:229], off
	v_lshl_add_u64 v[228:229], s[58:59], 0, v[148:149]
	s_mov_b32 m0, s67
	s_nop 0
	global_load_lds_dwordx4 v[228:229], off
	s_waitcnt vmcnt(8)
	s_waitcnt lgkmcnt(0)
	s_barrier
; #define PG8_STAGE(bufoff, gbase, voff) do { _Pragma("unroll") for (int _i = 0; _i < 2; ++_i) \
;         __builtin_amdgcn_global_load_lds((const unsigned*)((const char*)(gbase) + (voff)[_i]), (PG8_LAS unsigned*)(lds + (bufoff) + ldsw + _i * 8192), 16, 0, 0); } while (0)
; #define PG8_LDA(dst, b, h) do { _Pragma("unroll") for (int m = 0; m < 4; ++m) _Pragma("unroll") for (int k = 0; k < 2; ++k) dst[m][k] = *(const PG8_LAS bf16x8*)(lds + PG8_SA(b, h) + aoff + m * 2048 + k * 1024); } while (0)
; #define PG8_LDB(dst, b, h) do { _Pragma("unroll") for (int n = 0; n < 2; ++n) _Pragma("unroll") for (int k = 0; k < 2; ++k) dst[n][k] = *(const PG8_LAS bf16x8*)(lds + PG8_SB(b, h) + boff + n * 2048 + k * 1024); } while (0)
; #define PG8_MMA(ai, bj, At, Bt) do { __builtin_amdgcn_s_setprio(1); _Pragma("unroll") for (int m = 0; m < 4; ++m) _Pragma("unroll") for (int n = 0; n < 2; ++n) _Pragma("unroll") for (int k = 0; k < 2; ++k) \
;         acc[ai][bj][m][n] = __builtin_amdgcn_mfma_f32_16x16x32_bf16(Bt[n][k], At[m][k], acc[ai][bj][m][n], 0, 0, 0); __builtin_amdgcn_s_setprio(0); } while (0)
; #define PG8_WAIT_V(n) asm volatile("s_waitcnt vmcnt(" #n ")" ::: "memory")
; #define PG8_WAIT_L(n) asm volatile("s_waitcnt lgkmcnt(" #n ")" ::: "memory")
; #define PG8_BAR __builtin_amdgcn_s_barrier()
; #define PG8_SCHED __builtin_amdgcn_sched_barrier(0)
; template <class Epi, class Sched, bool ALIGN_EPI = false, bool SP2 = false, bool ATILED = false, bool BTILED = false>
; __device__ __forceinline__ void gemm_phase(PG8_LAS unsigned char* lds, const Gemm g, const Sched& S, const Epi& E, const int tid) {
;     ...
;             PG8_WAIT_V(8); PG8_WAIT_L(0); PG8_BAR; PG8_MMA(1, 0, At, B0); PG8_MMA(1, 1, At, B1); PG8_BAR; PG8_SCHED;
;             PG8_LDB(B0, 1, 0); PG8_LDB(B1, 1, 1); PG8_SCHED; PG8_LDA(At, 1, 0); PG8_STAGE(PG8_SA(0, 1), a2 + hstepA, voffA);
;             PG8_WAIT_V(8); PG8_WAIT_L(0); PG8_BAR; PG8_MMA(0, 0, At, B0); PG8_MMA(0, 1, At, B1); PG8_BAR; PG8_SCHED;
	s_setprio 1
	s_waitcnt lgkmcnt(0)
	v_mfma_f32_16x16x32_bf16 v[62:65], v[66:69], v[200:203], v[62:65]
	v_mfma_f32_16x16x32_bf16 v[54:57], v[78:81], v[200:203], v[54:57]
	v_mfma_f32_16x16x32_bf16 v[46:49], v[66:69], v[208:211], v[46:49]
	v_mfma_f32_16x16x32_bf16 v[38:41], v[78:81], v[208:211], v[38:41]
	v_mfma_f32_16x16x32_bf16 v[30:33], v[66:69], v[216:219], v[30:33]
	v_mfma_f32_16x16x32_bf16 v[22:25], v[78:81], v[216:219], v[22:25]
	v_mfma_f32_16x16x32_bf16 v[14:17], v[66:69], v[224:227], v[14:17]
	v_mfma_f32_16x16x32_bf16 v[6:9], v[78:81], v[224:227], v[6:9]
	v_mfma_f32_16x16x32_bf16 v[62:65], v[70:73], v[204:207], v[62:65]
	v_mfma_f32_16x16x32_bf16 v[54:57], v[82:85], v[204:207], v[54:57]
	v_mfma_f32_16x16x32_bf16 v[46:49], v[70:73], v[212:215], v[46:49]
	v_mfma_f32_16x16x32_bf16 v[38:41], v[82:85], v[212:215], v[38:41]
	v_mfma_f32_16x16x32_bf16 v[30:33], v[70:73], v[220:223], v[30:33]
	v_mfma_f32_16x16x32_bf16 v[22:25], v[82:85], v[220:223], v[22:25]
	v_mfma_f32_16x16x32_bf16 v[14:17], v[70:73], v[242:245], v[14:17]
	v_mfma_f32_16x16x32_bf16 v[6:9], v[82:85], v[242:245], v[6:9]
	s_setprio 0
	s_setprio 1
	v_mfma_f32_16x16x32_bf16 v[58:61], v[180:183], v[200:203], v[58:61]
	v_mfma_f32_16x16x32_bf16 v[50:53], v[190:193], v[200:203], v[50:53]
	v_mfma_f32_16x16x32_bf16 v[42:45], v[180:183], v[208:211], v[42:45]
	v_mfma_f32_16x16x32_bf16 v[34:37], v[190:193], v[208:211], v[34:37]
	v_mfma_f32_16x16x32_bf16 v[26:29], v[180:183], v[216:219], v[26:29]
	v_mfma_f32_16x16x32_bf16 v[18:21], v[190:193], v[216:219], v[18:21]
	v_mfma_f32_16x16x32_bf16 v[10:13], v[180:183], v[224:227], v[10:13]
	v_mfma_f32_16x16x32_bf16 v[2:5], v[190:193], v[224:227], v[2:5]
	v_mfma_f32_16x16x32_bf16 v[58:61], v[186:189], v[204:207], v[58:61]
	v_mfma_f32_16x16x32_bf16 v[50:53], v[196:199], v[204:207], v[50:53]
	v_mfma_f32_16x16x32_bf16 v[42:45], v[186:189], v[212:215], v[42:45]
	v_mfma_f32_16x16x32_bf16 v[34:37], v[196:199], v[212:215], v[34:37]
	v_mfma_f32_16x16x32_bf16 v[26:29], v[186:189], v[220:223], v[26:29]
	v_mfma_f32_16x16x32_bf16 v[18:21], v[196:199], v[220:223], v[18:21]
	v_mfma_f32_16x16x32_bf16 v[10:13], v[186:189], v[242:245], v[10:13]
	v_mfma_f32_16x16x32_bf16 v[2:5], v[196:199], v[242:245], v[2:5]
	s_setprio 0
	s_barrier
	s_add_i32 s77, 0, 0x18000
	s_add_i32 s78, 0, 0x1c000
	v_add_u32_e32 v82, s77, v1
	v_add_u32_e32 v195, s78, v1
	ds_read_b128 v[66:69], v82
	ds_read_b128 v[70:73], v82 offset:1024
	ds_read_b128 v[78:81], v82 offset:2048
	ds_read_b128 v[82:85], v82 offset:3072
	ds_read_b128 v[180:183], v195
	ds_read_b128 v[186:189], v195 offset:1024
	ds_read_b128 v[190:193], v195 offset:2048
	ds_read_b128 v[196:199], v195 offset:3072
	s_add_u32 s58, s58, 0x4000
	s_addc_u32 s59, s59, 0
	s_mov_b32 m0, s68
	v_lshl_add_u64 v[228:229], s[58:59], 0, v[152:153]
	ds_read_b128 v[200:203], v155 offset:32768
	ds_read_b128 v[204:207], v155 offset:33792
	ds_read_b128 v[208:211], v155 offset:34816
	ds_read_b128 v[212:215], v155 offset:35840
	ds_read_b128 v[216:219], v155 offset:36864
	ds_read_b128 v[220:223], v155 offset:37888
	ds_read_b128 v[224:227], v155 offset:38912
	ds_read_b128 v[242:245], v155 offset:39936
	global_load_lds_dwordx4 v[228:229], off
	v_lshl_add_u64 v[228:229], s[58:59], 0, v[148:149]
	s_mov_b32 m0, s69
	s_nop 0
	global_load_lds_dwordx4 v[228:229], off
	s_waitcnt vmcnt(8)
	s_waitcnt lgkmcnt(0)
	s_barrier
; #define PG8_STAGE(bufoff, gbase, voff) do { _Pragma("unroll") for (int _i = 0; _i < 2; ++_i) \
;         __builtin_amdgcn_global_load_lds((const unsigned*)((const char*)(gbase) + (voff)[_i]), (PG8_LAS unsigned*)(lds + (bufoff) + ldsw + _i * 8192), 16, 0, 0); } while (0)
; #define PG8_LDA(dst, b, h) do { _Pragma("unroll") for (int m = 0; m < 4; ++m) _Pragma("unroll") for (int k = 0; k < 2; ++k) dst[m][k] = *(const PG8_LAS bf16x8*)(lds + PG8_SA(b, h) + aoff + m * 2048 + k * 1024); } while (0)
; #define PG8_MMA(ai, bj, At, Bt) do { __builtin_amdgcn_s_setprio(1); _Pragma("unroll") for (int m = 0; m < 4; ++m) _Pragma("unroll") for (int n = 0; n < 2; ++n) _Pragma("unroll") for (int k = 0; k < 2; ++k) \
;         acc[ai][bj][m][n] = __builtin_amdgcn_mfma_f32_16x16x32_bf16(Bt[n][k], At[m][k], acc[ai][bj][m][n], 0, 0, 0); __builtin_amdgcn_s_setprio(0); } while (0)
; #define PG8_WAIT_V(n) asm volatile("s_waitcnt vmcnt(" #n ")" ::: "memory")
; #define PG8_WAIT_L(n) asm volatile("s_waitcnt lgkmcnt(" #n ")" ::: "memory")
; #define PG8_BAR __builtin_amdgcn_s_barrier()
; #define PG8_SCHED __builtin_amdgcn_sched_barrier(0)
; #define GAS __attribute__((address_space(1)))
; template <class Epi, class Sched, bool ALIGN_EPI = false, bool SP2 = false, bool ATILED = false, bool BTILED = false>
; __device__ __forceinline__ void gemm_phase(PG8_LAS unsigned char* lds, const Gemm g, const Sched& S, const Epi& E, const int tid) {
;     ...
;             PG8_WAIT_V(8); PG8_WAIT_L(0); PG8_BAR; PG8_MMA(0, 0, At, B0); PG8_MMA(0, 1, At, B1); PG8_BAR; PG8_SCHED;
;             PG8_LDA(At, 1, 1); PG8_STAGE(PG8_SB(1, 0), b3, voffB); PG8_STAGE(PG8_SB(1, 1), b3 + hstepB, voffB); PG8_STAGE(PG8_SA(1, 0), a3, voffA);
;             PG8_WAIT_V(8); PG8_WAIT_L(0); PG8_BAR; PG8_MMA(1, 0, At, B0); PG8_MMA(1, 1, At, B1); PG8_BAR; PG8_SCHED;
;     __device__ __forceinline__ void operator()(const f32x4 (&acc)[2][2][4][2], const pg8::Unit& u, int wr, int wc, int fr, int fq) const {
;     ...
;             for (int n = 0; n < 2; ++n) sh[bj][n] = *(const GAS f32x4*)(shW + 256 * u.pn + 128 * bj + 32 * wc + 8 * fq + 4 * n);
;         const int row0 = 256 * u.pm + 64 * wr + fr;
;         float rs[2][4];
; #pragma unroll
;         for (int ai = 0; ai < 2; ++ai)
; #pragma unroll
;             for (int m = 0; m < 4; ++m) rs[ai][m] = (float)ssq[row0 + 128 * ai + 16 * m] * (1.0f / 1024.0f);
	s_setprio 1
	s_waitcnt lgkmcnt(0)
	v_mfma_f32_16x16x32_bf16 v[142:145], v[66:69], v[200:203], v[142:145]
	v_mfma_f32_16x16x32_bf16 v[138:141], v[78:81], v[200:203], v[138:141]
	v_mfma_f32_16x16x32_bf16 v[126:129], v[66:69], v[208:211], v[126:129]
	v_mfma_f32_16x16x32_bf16 v[118:121], v[78:81], v[208:211], v[118:121]
	v_mfma_f32_16x16x32_bf16 v[110:113], v[66:69], v[216:219], v[110:113]
	v_mfma_f32_16x16x32_bf16 v[102:105], v[78:81], v[216:219], v[102:105]
	v_mfma_f32_16x16x32_bf16 v[94:97], v[66:69], v[224:227], v[94:97]
	v_mfma_f32_16x16x32_bf16 v[86:89], v[78:81], v[224:227], v[86:89]
	v_mfma_f32_16x16x32_bf16 v[142:145], v[70:73], v[204:207], v[142:145]
	v_mfma_f32_16x16x32_bf16 v[138:141], v[82:85], v[204:207], v[138:141]
	v_mfma_f32_16x16x32_bf16 v[126:129], v[70:73], v[212:215], v[126:129]
	v_mfma_f32_16x16x32_bf16 v[118:121], v[82:85], v[212:215], v[118:121]
	v_mfma_f32_16x16x32_bf16 v[110:113], v[70:73], v[220:223], v[110:113]
	v_mfma_f32_16x16x32_bf16 v[102:105], v[82:85], v[220:223], v[102:105]
	v_mfma_f32_16x16x32_bf16 v[94:97], v[70:73], v[242:245], v[94:97]
	v_mfma_f32_16x16x32_bf16 v[86:89], v[82:85], v[242:245], v[86:89]
	s_setprio 0
	s_setprio 1
	v_mfma_f32_16x16x32_bf16 v[134:137], v[180:183], v[200:203], v[134:137]
	v_mfma_f32_16x16x32_bf16 v[130:133], v[190:193], v[200:203], v[130:133]
	v_mfma_f32_16x16x32_bf16 v[122:125], v[180:183], v[208:211], v[122:125]
	v_mfma_f32_16x16x32_bf16 v[114:117], v[190:193], v[208:211], v[114:117]
	v_mfma_f32_16x16x32_bf16 v[106:109], v[180:183], v[216:219], v[106:109]
	v_mfma_f32_16x16x32_bf16 v[98:101], v[190:193], v[216:219], v[98:101]
	v_mfma_f32_16x16x32_bf16 v[90:93], v[180:183], v[224:227], v[90:93]
	v_mfma_f32_16x16x32_bf16 v[74:77], v[190:193], v[224:227], v[74:77]
	v_mfma_f32_16x16x32_bf16 v[134:137], v[186:189], v[204:207], v[134:137]
	v_mfma_f32_16x16x32_bf16 v[130:133], v[196:199], v[204:207], v[130:133]
	v_mfma_f32_16x16x32_bf16 v[122:125], v[186:189], v[212:215], v[122:125]
	v_mfma_f32_16x16x32_bf16 v[114:117], v[196:199], v[212:215], v[114:117]
	v_mfma_f32_16x16x32_bf16 v[106:109], v[186:189], v[220:223], v[106:109]
	v_mfma_f32_16x16x32_bf16 v[98:101], v[196:199], v[220:223], v[98:101]
	v_mfma_f32_16x16x32_bf16 v[90:93], v[186:189], v[242:245], v[90:93]
	v_mfma_f32_16x16x32_bf16 v[74:77], v[196:199], v[242:245], v[74:77]
	s_setprio 0
	s_barrier
	s_add_u32 s58, s56, 0x8000
	s_addc_u32 s59, s57, 0
	s_add_i32 s77, s77, s64
	v_lshl_add_u64 v[228:229], s[58:59], 0, v[150:151]
	s_mov_b32 m0, s77
	ds_read_b128 v[200:203], v155 offset:49152
	ds_read_b128 v[204:207], v155 offset:50176
	ds_read_b128 v[208:211], v155 offset:51200
	ds_read_b128 v[212:215], v155 offset:52224
	ds_read_b128 v[216:219], v155 offset:53248
	ds_read_b128 v[220:223], v155 offset:54272
	ds_read_b128 v[224:227], v155 offset:55296
	ds_read_b128 v[242:245], v155 offset:56320
	global_load_lds_dwordx4 v[228:229], off
	s_add_i32 m0, s77, 0x2000
	s_add_u32 s56, s56, 0xc000
	v_lshl_add_u64 v[228:229], s[58:59], 0, v[146:147]
	s_addc_u32 s57, s57, 0
	s_add_i32 s58, s78, s64
	global_load_lds_dwordx4 v[228:229], off
	v_lshl_add_u64 v[228:229], s[56:57], 0, v[150:151]
	s_mov_b32 m0, s58
	s_nop 0
	global_load_lds_dwordx4 v[228:229], off
	v_lshl_add_u64 v[228:229], s[56:57], 0, v[146:147]
	s_add_i32 m0, s58, 0x2000
	s_nop 0
	global_load_lds_dwordx4 v[228:229], off
	v_lshl_add_u64 v[228:229], s[54:55], 0, v[152:153]
	s_mov_b32 m0, s70
	s_nop 0
	global_load_lds_dwordx4 v[228:229], off
	v_lshl_add_u64 v[228:229], s[54:55], 0, v[148:149]
	s_mov_b32 m0, s71
	s_nop 0
	global_load_lds_dwordx4 v[228:229], off
	s_waitcnt vmcnt(8)
	s_cmp_lg_u32 s76, 12
	s_cbranch_scc1 .Lgu_touch_skip
	v_lshl_add_u32 v253, s28, 8, v154
	v_lshlrev_b32_e32 v253, 2, v253
	global_load_dword v252, v253, s[4:5]
	global_load_dword v252, v253, s[4:5] offset:128
	global_load_dword v252, v253, s[4:5] offset:512
	global_load_dword v252, v253, s[4:5] offset:640
	s_lshl_b32 s98, s18, 10
	s_mov_b32 s99, 0
	v_lshl_add_u64 v[248:249], s[98:99], 0, v[172:173]
	global_load_dword v252, v[248:249], off
	global_load_dword v252, v[248:249], off offset:512
